# attention tile loop: 5 VALU fewer per tile (row+32 staging addresses via immediate offset instead of three flipped registers; row-sum openings without the add of zero)
# speedup vs baseline: 1.0062x; 1.0005x over previous
; DEVI void attn_item(const P& p, int item, char* smem) {
;     ...
;             __syncthreads();
; #pragma unroll
;             for (int i = 0; i < 2; ++i) {
;                 const int row = (tid >> 3) + 32 * i, ch = tid & 7;
;                 const uint4 kv = *(const uint4*)(KB + ((size_t)(b * TPB + tok0 + row)) * 256 + kvh * 64 + ch * 8);
;                 *(uint4*)(sK + row * 128 + ((ch ^ (row & 7)) << 4)) = kv;
;     ...
;                 float mx = s[0][0];
; #pragma unroll
;                 for (int n = 0; n < 4; ++n)
; #pragma unroll
;                     for (int j = 0; j < 4; ++j) mx = fmaxf(mx, s[n][j]);
;                 mx = rowmax4(mx);
;                 const float mnew = fmaxf(mrow[m], mx);
;                 const float alpha = __builtin_amdgcn_exp2f(mrow[m] - mnew);
;                 mrow[m] = mnew;
;                 float ls = 0.f;
; #pragma unroll
;                 for (int n = 0; n < 4; ++n)
; #pragma unroll
;                     for (int j = 0; j < 4; ++j) { s[n][j] = __builtin_amdgcn_exp2f(s[n][j] - mnew); ls += s[n][j]; }
;                 lrow[m] = lrow[m] * alpha + ls;
; #pragma unroll
;                 for (int nd = 0; nd < 4; ++nd) O[nd][m] *= alpha;
; #pragma unroll
;                 for (int kk = 0; kk < 2; ++kk) {
;                     union { uint4 u; bf16x8 v; } cv;
;                     cv.u.x = pk2(s[2 * kk][0], s[2 * kk][1]); cv.u.y = pk2(s[2 * kk][2], s[2 * kk][3]);
;                     cv.u.z = pk2(s[2 * kk + 1][0], s[2 * kk + 1][1]); cv.u.w = pk2(s[2 * kk + 1][2], s[2 * kk + 1][3]);
;                     Pf[m][kk] = cv.v;
;                 }
;             }
; #pragma unroll
;             for (int nd = 0; nd < 4; ++nd)
; #pragma unroll
;                 for (int kk = 0; kk < 2; ++kk) {
;                     const int row = 16 * nd + fr, x2 = 2 * ((row >> 1) & 7);
;                     const uint2 lo = *(const uint2*)(sV + row * 128 + (((8 * kk + fq) ^ x2) << 3));
;                     const uint2 hi = *(const uint2*)(sV + row * 128 + (((8 * kk + 4 + fq) ^ x2) << 3));
;                     union { uint4 u; bf16x8 v; } cv;
;                     cv.u.x = lo.x; cv.u.y = lo.y; cv.u.z = hi.x; cv.u.w = hi.y;
; #pragma unroll
;                     for (int m = 0; m < 2; ++m) O[nd][m] = __builtin_amdgcn_mfma_f32_16x16x32_bf16(cv.v, Pf[m][kk], O[nd][m], 0, 0, 0);
.LBB0_1433:
	v_max3_f32 v91, v160, v86, v87
	v_sub_f32_e32 v0, v78, v91
	v_exp_f32_e32 v78, v0
	v_sub_f32_e32 v79, v79, v91
	v_exp_f32_e32 v79, v79
	v_sub_f32_e32 v80, v80, v91
	v_exp_f32_e32 v80, v80
	v_sub_f32_e32 v81, v81, v91
	v_exp_f32_e32 v81, v81
	v_sub_f32_e32 v74, v74, v91
	v_exp_f32_e32 v74, v74
	v_sub_f32_e32 v75, v75, v91
	v_add_f32_e32 v82, v79, v78
	v_exp_f32_e32 v75, v75
	v_sub_f32_e32 v76, v76, v91
	v_add_f32_e32 v82, v80, v82
	v_exp_f32_e32 v76, v76
	v_sub_f32_e32 v77, v77, v91
	v_add_f32_e32 v82, v81, v82
	v_exp_f32_e32 v77, v77
	v_sub_f32_e32 v58, v58, v91
	v_add_f32_e32 v82, v74, v82
	v_exp_f32_e32 v58, v58
	v_sub_f32_e32 v59, v59, v91
	v_add_f32_e32 v82, v75, v82
	v_exp_f32_e32 v59, v59
	v_add_f32_e32 v82, v76, v82
	v_add_f32_e32 v82, v77, v82
	v_add_f32_e32 v82, v58, v82
	v_sub_f32_e32 v50, v50, v91
	v_sub_f32_e32 v51, v51, v91
	v_exp_f32_e32 v83, v50
	v_add_f32_e32 v50, v59, v82
	v_exp_f32_e32 v82, v51
	v_sub_f32_e32 v51, v52, v91
	v_cvt_pk_bf16_f32 v52, v74, v75
	v_max_f32_e32 v74, v70, v71
	v_max3_f32 v74, v74, v72, v73
	v_max3_f32 v74, v74, v62, v63
	v_max3_f32 v74, v74, v64, v65
	v_max3_f32 v74, v74, v54, v55
	v_sub_f32_e32 v60, v60, v91
	v_max3_f32 v74, v74, v56, v57
	v_exp_f32_e32 v60, v60
	v_sub_f32_e32 v61, v61, v91
	v_max3_f32 v74, v74, v66, v67
	v_exp_f32_e32 v61, v61
	v_max3_f32 v74, v74, v68, v69
	v_mov_b32_e32 v75, v74
	s_nop 1
	v_permlane32_swap_b32_e32 v74, v75
	v_add_f32_e32 v50, v60, v50
	v_exp_f32_e32 v84, v51
	v_sub_f32_e32 v51, v53, v91
	v_sub_f32_e32 v0, v160, v91
	v_add_f32_e32 v50, v61, v50
	v_exp_f32_e32 v85, v51
	v_max_f32_e32 v74, v74, v75
	v_add_f32_e32 v50, v83, v50
	v_exp_f32_e32 v0, v0
	v_mov_b32_e32 v75, v74
	v_add_f32_e32 v50, v82, v50
	s_nop 0
	v_permlane16_swap_b32_e32 v74, v75
	v_add_f32_e32 v50, v84, v50
	v_max3_f32 v93, v159, v74, v75
	v_add_f32_e32 v92, v85, v50
	v_sub_f32_e32 v54, v54, v93
	v_fmac_f32_e32 v92, v158, v0
	v_exp_f32_e32 v158, v54
	v_sub_f32_e32 v54, v55, v93
	v_sub_f32_e32 v74, v159, v93
	v_exp_f32_e32 v159, v54
	v_sub_f32_e32 v54, v56, v93
	v_exp_f32_e32 v160, v54
	v_sub_f32_e32 v54, v57, v93
	v_sub_f32_e32 v62, v62, v93
	v_exp_f32_e32 v161, v54
	v_sub_f32_e32 v54, v66, v93
	v_exp_f32_e32 v94, v62
	v_sub_f32_e32 v62, v63, v93
	v_exp_f32_e32 v162, v54
	v_sub_f32_e32 v54, v67, v93
	v_exp_f32_e32 v95, v62
	v_sub_f32_e32 v62, v64, v93
	v_exp_f32_e32 v163, v54
	v_sub_f32_e32 v54, v68, v93
	v_exp_f32_e32 v96, v62
	v_sub_f32_e32 v62, v65, v93
	v_exp_f32_e32 v164, v54
	v_sub_f32_e32 v54, v69, v93
	v_exp_f32_e32 v97, v62
	v_exp_f32_e32 v165, v54
	ds_read_b128 v[54:57], v132 offset:8192
	ds_read_b128 v[62:65], v132 offset:10240
	v_sub_f32_e32 v70, v70, v93
	v_exp_f32_e32 v86, v70
	v_sub_f32_e32 v70, v71, v93
	v_exp_f32_e32 v87, v70
	v_sub_f32_e32 v70, v72, v93
	v_cvt_pk_bf16_f32 v50, v78, v79
	v_cvt_pk_bf16_f32 v51, v80, v81
	v_cvt_pk_bf16_f32 v53, v76, v77
	v_exp_f32_e32 v88, v70
	v_sub_f32_e32 v70, v73, v93
	v_exp_f32_e32 v90, v74
	ds_read_b128 v[74:77], v134 offset:8192
	ds_read_b128 v[78:81], v134 offset:10240
	v_exp_f32_e32 v89, v70
	s_waitcnt lgkmcnt(3)
	s_waitcnt lgkmcnt(2)
	v_mul_f32_e32 v40, v0, v40
	v_mul_f32_e32 v41, v0, v41
	v_mul_f32_e32 v38, v0, v38
	v_mul_f32_e32 v39, v0, v39
	v_mul_f32_e32 v44, v0, v44
	v_mul_f32_e32 v45, v0, v45
	v_mul_f32_e32 v42, v0, v42
	v_mul_f32_e32 v43, v0, v43
	v_cvt_pk_bf16_f32 v58, v58, v59
	v_cvt_pk_bf16_f32 v59, v60, v61
	v_cvt_pk_bf16_f32 v60, v83, v82
	v_cvt_pk_bf16_f32 v61, v84, v85
	v_mul_f32_e32 v16, v90, v16
	v_mul_f32_e32 v17, v90, v17
	v_mul_f32_e32 v14, v90, v14
	v_mul_f32_e32 v15, v90, v15
	v_cvt_pk_bf16_f32 v66, v86, v87
	v_cvt_pk_bf16_f32 v67, v88, v89
	v_cvt_pk_bf16_f32 v68, v94, v95
	v_cvt_pk_bf16_f32 v69, v96, v97
	s_waitcnt lgkmcnt(1)
	s_waitcnt lgkmcnt(0)
	v_mul_f32_e32 v12, v90, v12
	v_mul_f32_e32 v13, v90, v13
	v_mul_f32_e32 v10, v90, v10
	v_mul_f32_e32 v11, v90, v11
	v_mul_f32_e32 v48, v0, v48
	v_mul_f32_e32 v49, v0, v49
	v_mul_f32_e32 v46, v0, v46
	v_mul_f32_e32 v47, v0, v47
	v_mfma_f32_16x16x32_bf16 v[38:41], v[54:57], v[50:53], v[38:41]
	v_mul_f32_e64 v20, v20, v0
	v_mul_f32_e64 v21, v21, v0
	v_mul_f32_e32 v18, v0, v18
	v_mul_f32_e32 v19, v0, v19
	v_mfma_f32_16x16x32_bf16 v[14:17], v[54:57], v[66:69], v[14:17]
	ds_read_b128 v[54:57], v132 offset:12288
	v_add_f32_e32 v0, v87, v86
	v_add_f32_e32 v0, v88, v0
	v_mfma_f32_16x16x32_bf16 v[42:45], v[62:65], v[50:53], v[42:45]
	v_cvt_pk_bf16_f32 v70, v158, v159
	v_cvt_pk_bf16_f32 v71, v160, v161
	v_cvt_pk_bf16_f32 v72, v162, v163
	v_mfma_f32_16x16x32_bf16 v[10:13], v[62:65], v[66:69], v[10:13]
	ds_read_b128 v[62:65], v132 offset:14336
	v_cvt_pk_bf16_f32 v73, v164, v165
	v_add_f32_e32 v0, v89, v0
	v_mfma_f32_16x16x32_bf16 v[38:41], v[74:77], v[58:61], v[38:41]
	v_add_f32_e32 v0, v94, v0
	s_waitcnt lgkmcnt(1)
	v_mfma_f32_16x16x32_bf16 v[14:17], v[74:77], v[70:73], v[14:17]
	ds_read_b128 v[74:77], v134 offset:12288
	s_waitcnt lgkmcnt(1)
	v_mfma_f32_16x16x32_bf16 v[42:45], v[78:81], v[58:61], v[42:45]
	v_add_f32_e32 v0, v95, v0
	v_mfma_f32_16x16x32_bf16 v[10:13], v[78:81], v[70:73], v[10:13]
	ds_read_b128 v[78:81], v134 offset:14336
	v_add_f32_e32 v0, v96, v0
	v_add_f32_e32 v0, v97, v0
	v_add_f32_e32 v0, v158, v0
	v_mul_f32_e32 v8, v90, v8
	v_mul_f32_e32 v9, v90, v9
	v_mul_f32_e32 v6, v90, v6
	v_mul_f32_e32 v7, v90, v7
	s_waitcnt lgkmcnt(0)
	v_xor_b32_e32 v133, 0x4000, v133
	v_xor_b32_e32 v135, 0x4000, v135
	v_xor_b32_e32 v214, 0x4000, v214
	s_cmp_eq_u32 s99, 1
	s_cbranch_scc0 .Lat_endw2
	s_waitcnt vmcnt(0)
	ds_write_b128 v133, v[190:193]
	ds_write_b64 v135, v[194:195] offset:8192
	ds_write_b64 v214, v[196:197] offset:8192
	ds_write_b128 v133, v[198:201] offset:4096
	ds_write_b64 v135, v[202:203] offset:12288
	ds_write_b64 v214, v[204:205] offset:12288
	s_mov_b32 s99, 2

; DEVI void attn_item(const P& p, int item, char* smem) {
;     ...
;             __syncthreads();
; #pragma unroll
;             for (int i = 0; i < 2; ++i) {
;                 const int row = (tid >> 3) + 32 * i, ch = tid & 7;
;                 const uint4 kv = *(const uint4*)(KB + ((size_t)(b * TPB + tok0 + row)) * 256 + kvh * 64 + ch * 8);
;                 *(uint4*)(sK + row * 128 + ((ch ^ (row & 7)) << 4)) = kv;
;                 const uint4 vv = *(const uint4*)(VT + ((size_t)(b * 256 + kvh * 64 + row)) * TPB + tok0 + ch * 8);
;                 *(uint4*)(sV + row * 128 + ((ch ^ ((row >> 1) & 7)) << 4)) = vv;
;             }
;             __syncthreads();
.LBB0_1439:
	s_andn2_b64 vcc, exec, s[4:5]
	s_cbranch_vccnz .LBB0_1434
	s_ashr_i32 s31, s30, 31
	s_cmp_eq_u32 s99, 2
	s_cbranch_scc1 .Lat_inlds
	s_mov_b32 s101, 0
	v_lshl_add_u64 v[58:59], s[30:31], 1, v[100:101]
	v_lshl_add_u64 v[54:55], v[58:59], 0, v[114:115]
	v_lshl_add_u64 v[62:63], v[58:59], 0, v[116:117]
	s_add_i32 s100, s30, s46
	s_lshl_b32 s100, s100, 9
	v_lshl_add_u64 v[50:51], v[226:227], 0, s[100:101]
	s_add_i32 s100, s100, 0x4000
	v_lshl_add_u64 v[60:61], v[226:227], 0, s[100:101]
	global_load_dwordx4 v[190:193], v[50:51], off
	global_load_dwordx4 v[194:197], v[54:55], off
	global_load_dwordx4 v[198:201], v[60:61], off
	global_load_dwordx4 v[202:205], v[62:63], off
	s_waitcnt vmcnt(0)
	ds_write_b128 v133, v[190:193]
	ds_write_b64 v135, v[194:195] offset:8192
	ds_write_b64 v214, v[196:197] offset:8192
	ds_write_b128 v133, v[198:201] offset:4096
	ds_write_b64 v135, v[202:203] offset:12288
	ds_write_b64 v214, v[204:205] offset:12288
	s_waitcnt lgkmcnt(0)
	s_barrier
